# diff-attention tile loop: MFMA-VALU interleave - PV MFMAs reordered 16-key-slice major so three of the four exp/sum/cvt groups run in the shadow of the previous slice's MFMAs; V fragments per slice in
# speedup vs baseline: 1.0148x; 1.0064x over previous
; #define LAS __attribute__((address_space(3)))
; __device__ __forceinline__ int crow(int r, int hi) { return (r & 3) + 8 * (r >> 2) + 4 * hi; }
; __device__ __forceinline__ s16x4 vtr(const LAS unsigned char* p) { return __builtin_bit_cast(s16x4, __builtin_amdgcn_ds_read_tr16_b64_v4i16((LAS v4i16_t*)p)); }
; template <int DQK, int DV, bool HAS_BIAS>
; __device__ __forceinline__ void attn_tile(AttnState<DQK, DV>& st, const LAS unsigned char* Kt, const LAS unsigned char* Vt, int bias_mode, const LAS float* tab, int rel0, int nkeys, bool first, LAS float* wsf, int lane) {
;     ...
;         p0 = __builtin_amdgcn_mfma_f32_32x32x16_bf16(ka[0], st.qf[0], p0, 0, 0, 0);
;         p1 = __builtin_amdgcn_mfma_f32_32x32x16_bf16(kb[0], st.qf[0], p1, 0, 0, 0);
;     } else {
;         p0 = __builtin_amdgcn_mfma_f32_32x32x16_bf16(ka[0], st.qf[0], st.negm, 0, 0, 0);
;         p1 = __builtin_amdgcn_mfma_f32_32x32x16_bf16(kb[0], st.qf[0], st.negm, 0, 0, 0);
;     }
; #pragma unroll
;     for (int ks = 1; ks < KS; ++ks) {
;         p0 = __builtin_amdgcn_mfma_f32_32x32x16_bf16(ka[ks], st.qf[ks], p0, 0, 0, 0);
;         p1 = __builtin_amdgcn_mfma_f32_32x32x16_bf16(kb[ks], st.qf[ks], p1, 0, 0, 0);
;     }
;     const int q4 = (lane & 15) >> 2, blk = (lane >> 4) & 1, pp = lane & 3;
;     const LAS unsigned char* vp = Vt + (4 * hi + q4) * PV + (16 * blk + 4 * pp) * 2;
;     s16x4 vlo[2][4], vhi[2][4];
; #pragma unroll
;     for (int s4 = 0; s4 < 4; ++s4) { vlo[0][s4] = vtr(vp + (16 * s4) * PV); vhi[0][s4] = vtr(vp + (16 * s4 + 8) * PV); }
;     __builtin_amdgcn_sched_barrier(0);
;     if (nkeys < 64) {
; #pragma unroll
;         for (int r = 0; r < 16; ++r) { const int k = crow(r, hi); if (k >= nkeys) p0[r] = -1e30f; if (k + 32 >= nkeys) p1[r] = -1e30f; }
;     }
;     float mxa = __builtin_fmaxf(__builtin_fmaxf(p0[0], p0[1]), p1[0]), mxb = __builtin_fmaxf(__builtin_fmaxf(p0[2], p0[3]), p1[1]);
;     mxa = __builtin_fmaxf(__builtin_fmaxf(mxa, p1[2]), p1[3]);
; #pragma unroll
;     for (int r = 4; r < 16; r += 4) {
;         mxa = __builtin_fmaxf(__builtin_fmaxf(mxa, p0[r]), p0[r + 1]); mxb = __builtin_fmaxf(__builtin_fmaxf(mxb, p0[r + 2]), p0[r + 3]);
;         mxa = __builtin_fmaxf(__builtin_fmaxf(mxa, p1[r]), p1[r + 1]); mxb = __builtin_fmaxf(__builtin_fmaxf(mxb, p1[r + 2]), p1[r + 3]);
;     }
;     const float mx = xmax32(__builtin_fmaxf(mxa, mxb));
.LBB0_527:
	s_waitcnt vmcnt(5) lgkmcnt(6)
	v_mfma_f32_32x32x16_bf16 v[80:95], v[160:163], v[116:119], v[80:95]
	s_cmp_eq_u32 s58, 0
	s_cselect_b64 s[2:3], -1, 0
	s_cmp_lg_u32 s58, 0
	s_waitcnt lgkmcnt(4)
	v_mfma_f32_32x32x16_bf16 v[96:111], v[164:167], v[116:119], v[96:111]
	s_waitcnt vmcnt(4) lgkmcnt(3)
	v_mfma_f32_32x32x16_bf16 v[80:95], v[156:159], v[120:123], v[80:95]
	s_waitcnt lgkmcnt(1)
	v_mfma_f32_32x32x16_bf16 v[96:111], v[172:175], v[120:123], v[96:111]
	s_waitcnt vmcnt(3)
	v_mfma_f32_32x32x16_bf16 v[80:95], v[152:155], v[124:127], v[80:95]
	ds_read_b64_tr_b16 v[152:153], v217 offset:17408
	ds_read_b64_tr_b16 v[154:155], v217 offset:19968
	ds_read_b64_tr_b16 v[156:157], v217 offset:17472
	ds_read_b64_tr_b16 v[158:159], v217 offset:20032
	ds_read_b64_tr_b16 v[160:161], v217 offset:17536
	ds_read_b64_tr_b16 v[162:163], v217 offset:20096
	ds_read_b64_tr_b16 v[164:165], v217 offset:17600
	ds_read_b64_tr_b16 v[166:167], v217 offset:20160
	s_waitcnt lgkmcnt(8)
	v_mfma_f32_32x32x16_bf16 v[96:111], v[168:171], v[124:127], v[96:111]
	ds_read_b64_tr_b16 v[226:227], v217 offset:22528
	ds_read_b64_tr_b16 v[228:229], v217 offset:25088
	ds_read_b64_tr_b16 v[230:231], v217 offset:22592
	ds_read_b64_tr_b16 v[232:233], v217 offset:25152
	ds_read_b64_tr_b16 v[234:235], v217 offset:22656
	ds_read_b64_tr_b16 v[236:237], v217 offset:25216
	ds_read_b64_tr_b16 v[238:239], v217 offset:22720
	ds_read_b64_tr_b16 v[240:241], v217 offset:25280
	s_nop 1
	v_max_f32_e32 v168, v81, v81
	v_max_f32_e32 v169, v80, v80
	v_max_f32_e32 v168, v169, v168
	s_nop 6
	v_max3_f32 v169, v82, v83, v97
	v_max3_f32 v168, v168, v96, v98
	v_max3_f32 v168, v168, v99, v84
	v_max3_f32 v169, v169, v86, v87
	v_max3_f32 v168, v168, v85, v100
	v_max3_f32 v169, v169, v102, v103
	v_max3_f32 v168, v168, v101, v88
	v_max3_f32 v169, v169, v90, v91
	v_max3_f32 v168, v168, v89, v104
	v_max3_f32 v169, v169, v106, v107
	v_max3_f32 v168, v168, v105, v92
	v_max3_f32 v169, v169, v94, v95
	v_max3_f32 v168, v168, v93, v108
	v_max3_f32 v169, v169, v110, v111
	v_max3_f32 v168, v168, v109, v169
	v_mov_b32_e32 v169, v168
	s_nop 1
	v_permlane32_swap_b32_e32 v168, v169
	v_max_f32_e32 v169, v169, v169
	v_max_f32_e32 v168, v168, v168
	v_max_f32_e32 v168, v168, v169
	s_cbranch_scc0 .LBB0_529
	v_cmp_lt_f32_e32 vcc, s77, v168
	s_cmp_lg_u64 vcc, 0
	s_cselect_b64 s[44:45], -1, 0
	s_cbranch_execz .LBB0_530
	s_branch .LBB0_531

; __device__ __forceinline__ s16x4 vtr(const LAS unsigned char* p) { return __builtin_bit_cast(s16x4, __builtin_amdgcn_ds_read_tr16_b64_v4i16((LAS v4i16_t*)p)); }
; template <int DQK, int DV, bool HAS_BIAS>
; __device__ __forceinline__ void attn_tile(AttnState<DQK, DV>& st, const LAS unsigned char* Kt, const LAS unsigned char* Vt, int bias_mode, const LAS float* tab, int rel0, int nkeys, bool first, LAS float* wsf, int lane) {
;     ...
;     float sum0 = 0.f, sum1 = 0.f;
; #pragma unroll
;     for (int r = 0; r < 16; ++r) { p0[r] = __builtin_amdgcn_exp2f(p0[r]); p1[r] = __builtin_amdgcn_exp2f(p1[r]); sum0 += p0[r]; sum1 += p1[r]; }
;     st.l += sum0 + sum1;
;     bf16x8 pf[4];
;     pf[0] = pack8(p0[0], p0[1], p0[2], p0[3], p0[4], p0[5], p0[6], p0[7]);
;     pf[1] = pack8(p0[8], p0[9], p0[10], p0[11], p0[12], p0[13], p0[14], p0[15]);
;     pf[2] = pack8(p1[0], p1[1], p1[2], p1[3], p1[4], p1[5], p1[6], p1[7]);
;     pf[3] = pack8(p1[8], p1[9], p1[10], p1[11], p1[12], p1[13], p1[14], p1[15]);
;     __builtin_amdgcn_sched_barrier(0);
; #pragma unroll
;     for (int db = 0; db < NDB; ++db) {
;         if (db + 1 < NDB) {
; #pragma unroll
;             for (int s4 = 0; s4 < 4; ++s4) { vlo[(db + 1) & 1][s4] = vtr(vp + (16 * s4) * PV + (db + 1) * 64); vhi[(db + 1) & 1][s4] = vtr(vp + (16 * s4 + 8) * PV + (db + 1) * 64); }
;         }
; #pragma unroll
;         for (int s4 = 0; s4 < 4; ++s4) {
;             const s16x4 lo = vlo[db & 1][s4], h4 = vhi[db & 1][s4];
;             const bf16x8 vb = {lo[0], lo[1], lo[2], lo[3], h4[0], h4[1], h4[2], h4[3]};
;             st.o[db] = __builtin_amdgcn_mfma_f32_32x32x16_bf16(pf[s4], vb, st.o[db], 0, 0, 0);
;         }
;         __builtin_amdgcn_sched_barrier(0);
;     }
.LBB0_535:
	v_exp_f32_e32 v168, v80
	v_exp_f32_e32 v169, v81
	v_add_f32_e32 v222, 0, v168
	v_exp_f32_e32 v170, v82
	v_add_f32_e32 v222, v169, v222
	v_exp_f32_e32 v171, v83
	v_add_f32_e32 v222, v170, v222
	v_exp_f32_e32 v172, v84
	v_add_f32_e32 v222, v171, v222
	v_exp_f32_e32 v173, v85
	v_add_f32_e32 v222, v172, v222
	v_exp_f32_e32 v174, v86
	v_add_f32_e32 v222, v173, v222
	v_exp_f32_e32 v175, v87
	v_add_f32_e32 v222, v174, v222
	v_cvt_pk_bf16_f32 v80, v168, v169
	v_add_f32_e32 v222, v175, v222
	v_cvt_pk_bf16_f32 v81, v170, v171
	v_cvt_pk_bf16_f32 v82, v172, v173
	v_cvt_pk_bf16_f32 v83, v174, v175
	s_nop 1
	s_waitcnt lgkmcnt(8)
	v_mfma_f32_32x32x16_bf16 v[48:63], v[80:83], v[152:155], v[48:63]
	v_exp_f32_e32 v176, v88
	v_exp_f32_e32 v177, v89
	v_add_f32_e32 v222, v176, v222
	v_exp_f32_e32 v178, v90
	v_add_f32_e32 v222, v177, v222
	v_mfma_f32_32x32x16_bf16 v[32:47], v[80:83], v[156:159], v[32:47]
	v_exp_f32_e32 v179, v91
	v_add_f32_e32 v222, v178, v222
	v_exp_f32_e32 v180, v92
	v_add_f32_e32 v222, v179, v222
	v_exp_f32_e32 v181, v93
	v_mfma_f32_32x32x16_bf16 v[16:31], v[80:83], v[160:163], v[16:31]
	v_add_f32_e32 v222, v180, v222
	v_exp_f32_e32 v182, v94
	v_add_f32_e32 v222, v181, v222
	v_exp_f32_e32 v183, v95
	v_add_f32_e32 v222, v182, v222
	v_mfma_f32_32x32x16_bf16 v[0:15], v[80:83], v[164:167], v[0:15]
	v_cvt_pk_bf16_f32 v84, v176, v177
	v_add_f32_e32 v222, v183, v222
	v_cvt_pk_bf16_f32 v85, v178, v179
	v_cvt_pk_bf16_f32 v86, v180, v181
	v_cvt_pk_bf16_f32 v87, v182, v183
	ds_read_b64_tr_b16 v[152:153], v217 offset:27648
	ds_read_b64_tr_b16 v[154:155], v217 offset:30208
	ds_read_b64_tr_b16 v[156:157], v217 offset:27712
	ds_read_b64_tr_b16 v[158:159], v217 offset:30272
	ds_read_b64_tr_b16 v[160:161], v217 offset:27776
	ds_read_b64_tr_b16 v[162:163], v217 offset:30336
	ds_read_b64_tr_b16 v[164:165], v217 offset:27840
	ds_read_b64_tr_b16 v[166:167], v217 offset:30400
	s_waitcnt lgkmcnt(8)
	v_mfma_f32_32x32x16_bf16 v[48:63], v[84:87], v[226:229], v[48:63]
	v_exp_f32_e32 v168, v96
	v_exp_f32_e32 v169, v97
	v_add_f32_e32 v223, 0, v168
	v_exp_f32_e32 v170, v98
	v_add_f32_e32 v223, v169, v223
	v_mfma_f32_32x32x16_bf16 v[32:47], v[84:87], v[230:233], v[32:47]
	v_exp_f32_e32 v171, v99
	v_add_f32_e32 v223, v170, v223
	v_exp_f32_e32 v172, v100
	v_add_f32_e32 v223, v171, v223
	v_exp_f32_e32 v173, v101
	v_mfma_f32_32x32x16_bf16 v[16:31], v[84:87], v[234:237], v[16:31]
	v_add_f32_e32 v223, v172, v223
	v_exp_f32_e32 v174, v102
	v_add_f32_e32 v223, v173, v223
	v_exp_f32_e32 v175, v103
	v_add_f32_e32 v223, v174, v223
	v_mfma_f32_32x32x16_bf16 v[0:15], v[84:87], v[238:241], v[0:15]
	v_cvt_pk_bf16_f32 v88, v168, v169
	v_add_f32_e32 v223, v175, v223
	v_cvt_pk_bf16_f32 v89, v170, v171
	v_cvt_pk_bf16_f32 v90, v172, v173
	v_cvt_pk_bf16_f32 v91, v174, v175
	ds_read_b64_tr_b16 v[226:227], v217 offset:32768
	ds_read_b64_tr_b16 v[228:229], v217 offset:35328
	ds_read_b64_tr_b16 v[230:231], v217 offset:32832
	ds_read_b64_tr_b16 v[232:233], v217 offset:35392
	ds_read_b64_tr_b16 v[234:235], v217 offset:32896
	ds_read_b64_tr_b16 v[236:237], v217 offset:35456
	ds_read_b64_tr_b16 v[238:239], v217 offset:32960
	ds_read_b64_tr_b16 v[240:241], v217 offset:35520
	s_waitcnt lgkmcnt(8)
	v_mfma_f32_32x32x16_bf16 v[48:63], v[88:91], v[152:155], v[48:63]
	v_exp_f32_e32 v176, v104
	v_exp_f32_e32 v177, v105
	v_add_f32_e32 v223, v176, v223
	v_exp_f32_e32 v178, v106
	v_add_f32_e32 v223, v177, v223
	v_mfma_f32_32x32x16_bf16 v[32:47], v[88:91], v[156:159], v[32:47]
	v_exp_f32_e32 v179, v107
	v_add_f32_e32 v223, v178, v223
	v_exp_f32_e32 v180, v108
	v_add_f32_e32 v223, v179, v223
	v_exp_f32_e32 v181, v109
	v_mfma_f32_32x32x16_bf16 v[16:31], v[88:91], v[160:163], v[16:31]
	v_add_f32_e32 v223, v180, v223
	v_exp_f32_e32 v182, v110
	v_add_f32_e32 v223, v181, v223
	v_exp_f32_e32 v183, v111
	v_add_f32_e32 v223, v182, v223
	v_mfma_f32_32x32x16_bf16 v[0:15], v[88:91], v[164:167], v[0:15]
	v_cvt_pk_bf16_f32 v92, v176, v177
	v_add_f32_e32 v223, v183, v223
	v_cvt_pk_bf16_f32 v93, v178, v179
	v_cvt_pk_bf16_f32 v94, v180, v181
	v_cvt_pk_bf16_f32 v95, v182, v183
	s_waitcnt lgkmcnt(0)
	v_mfma_f32_32x32x16_bf16 v[48:63], v[92:95], v[226:229], v[48:63]
	v_add_f32_e32 v222, v223, v222
	v_mfma_f32_32x32x16_bf16 v[32:47], v[92:95], v[230:233], v[32:47]
	v_add_f32_e32 v184, v184, v222
	v_mfma_f32_32x32x16_bf16 v[16:31], v[92:95], v[234:237], v[16:31]
	v_mfma_f32_32x32x16_bf16 v[0:15], v[92:95], v[238:241], v[0:15]

; template <int DQK, int DV, bool HAS_BIAS>
; __device__ __forceinline__ void attn_tile(AttnState<DQK, DV>& st, const LAS unsigned char* Kt, const LAS unsigned char* Vt, int bias_mode, const LAS float* tab, int rel0, int nkeys, bool first, LAS float* wsf, int lane) {
;     ...
;         p0 = __builtin_amdgcn_mfma_f32_32x32x16_bf16(ka[0], st.qf[0], p0, 0, 0, 0);
;         p1 = __builtin_amdgcn_mfma_f32_32x32x16_bf16(kb[0], st.qf[0], p1, 0, 0, 0);
;     } else {
;         p0 = __builtin_amdgcn_mfma_f32_32x32x16_bf16(ka[0], st.qf[0], st.negm, 0, 0, 0);
;         p1 = __builtin_amdgcn_mfma_f32_32x32x16_bf16(kb[0], st.qf[0], st.negm, 0, 0, 0);
;     }
; #pragma unroll
;     for (int ks = 1; ks < KS; ++ks) {
;         p0 = __builtin_amdgcn_mfma_f32_32x32x16_bf16(ka[ks], st.qf[ks], p0, 0, 0, 0);
;         p1 = __builtin_amdgcn_mfma_f32_32x32x16_bf16(kb[ks], st.qf[ks], p1, 0, 0, 0);
;     }
;     const int q4 = (lane & 15) >> 2, blk = (lane >> 4) & 1, pp = lane & 3;
;     const LAS unsigned char* vp = Vt + (4 * hi + q4) * PV + (16 * blk + 4 * pp) * 2;
;     s16x4 vlo[2][4], vhi[2][4];
; #pragma unroll
;     for (int s4 = 0; s4 < 4; ++s4) { vlo[0][s4] = vtr(vp + (16 * s4) * PV); vhi[0][s4] = vtr(vp + (16 * s4 + 8) * PV); }
;     __builtin_amdgcn_sched_barrier(0);
;     if (nkeys < 64) {
; #pragma unroll
;         for (int r = 0; r < 16; ++r) { const int k = crow(r, hi); if (k >= nkeys) p0[r] = -1e30f; if (k + 32 >= nkeys) p1[r] = -1e30f; }
;     }
;     float mxa = __builtin_fmaxf(__builtin_fmaxf(p0[0], p0[1]), p1[0]), mxb = __builtin_fmaxf(__builtin_fmaxf(p0[2], p0[3]), p1[1]);
;     mxa = __builtin_fmaxf(__builtin_fmaxf(mxa, p1[2]), p1[3]);
; #pragma unroll
;     for (int r = 4; r < 16; r += 4) {
;         mxa = __builtin_fmaxf(__builtin_fmaxf(mxa, p0[r]), p0[r + 1]); mxb = __builtin_fmaxf(__builtin_fmaxf(mxb, p0[r + 2]), p0[r + 3]);
;         mxa = __builtin_fmaxf(__builtin_fmaxf(mxa, p1[r]), p1[r + 1]); mxb = __builtin_fmaxf(__builtin_fmaxf(mxb, p1[r + 2]), p1[r + 3]);
;     }
;     const float mx = xmax32(__builtin_fmaxf(mxa, mxb));
;     if (first || __any(mx > ATT_THR)) {
;         const float dl = first ? mx : __builtin_fmaxf(mx, 0.f);
;         st.m += dl;
; #pragma unroll
;         for (int r = 0; r < 16; ++r) { st.negm[r] = -st.m; p0[r] -= dl; p1[r] -= dl; }
;         const float f = __builtin_amdgcn_exp2f(-dl);
;         st.l *= f;
.LBB0_547:
	s_waitcnt lgkmcnt(6)
	v_mfma_f32_32x32x16_bf16 v[80:95], v[160:163], v[116:119], v[80:95]
	s_waitcnt lgkmcnt(4)
	v_mfma_f32_32x32x16_bf16 v[96:111], v[164:167], v[116:119], v[96:111]
	s_waitcnt lgkmcnt(3)
	v_mfma_f32_32x32x16_bf16 v[80:95], v[156:159], v[120:123], v[80:95]
	s_waitcnt lgkmcnt(1)
	v_mfma_f32_32x32x16_bf16 v[96:111], v[172:175], v[120:123], v[96:111]
	v_mfma_f32_32x32x16_bf16 v[80:95], v[152:155], v[124:127], v[80:95]
	ds_read_b64_tr_b16 v[152:153], v217 offset:47104
	ds_read_b64_tr_b16 v[154:155], v217 offset:49664
	ds_read_b64_tr_b16 v[156:157], v217 offset:47168
	ds_read_b64_tr_b16 v[158:159], v217 offset:49728
	ds_read_b64_tr_b16 v[160:161], v217 offset:47232
	ds_read_b64_tr_b16 v[162:163], v217 offset:49792
	ds_read_b64_tr_b16 v[164:165], v217 offset:47296
	ds_read_b64_tr_b16 v[166:167], v217 offset:49856
	s_waitcnt lgkmcnt(8)
	v_mfma_f32_32x32x16_bf16 v[96:111], v[168:171], v[124:127], v[96:111]
	ds_read_b64_tr_b16 v[226:227], v217 offset:52224
	ds_read_b64_tr_b16 v[228:229], v217 offset:54784
	ds_read_b64_tr_b16 v[230:231], v217 offset:52288
	ds_read_b64_tr_b16 v[232:233], v217 offset:54848
	ds_read_b64_tr_b16 v[234:235], v217 offset:52352
	ds_read_b64_tr_b16 v[236:237], v217 offset:54912
	ds_read_b64_tr_b16 v[238:239], v217 offset:52416
	ds_read_b64_tr_b16 v[240:241], v217 offset:54976
	s_nop 1
	v_max_f32_e32 v168, v81, v81
	v_max_f32_e32 v169, v80, v80
	v_max_f32_e32 v168, v169, v168
	s_nop 6
	v_max3_f32 v169, v82, v83, v97
	v_max3_f32 v168, v168, v96, v98
	v_max3_f32 v168, v168, v99, v84
	v_max3_f32 v169, v169, v86, v87
	v_max3_f32 v168, v168, v85, v100
	v_max3_f32 v169, v169, v102, v103
	v_max3_f32 v168, v168, v101, v88
	v_max3_f32 v169, v169, v90, v91
	v_max3_f32 v168, v168, v89, v104
	v_max3_f32 v169, v169, v106, v107
	v_max3_f32 v168, v168, v105, v92
	v_max3_f32 v169, v169, v94, v95
	v_max3_f32 v168, v168, v93, v108
	v_max3_f32 v169, v169, v110, v111
	v_max3_f32 v168, v168, v109, v169
	v_mov_b32_e32 v169, v168
	s_nop 1
	v_permlane32_swap_b32_e32 v168, v169
	v_max_f32_e32 v169, v169, v169
	v_max_f32_e32 v168, v168, v168
	v_max_f32_e32 v168, v168, v169
	v_cmp_lt_f32_e32 vcc, s77, v168
	s_cbranch_vccz .LBB0_551
	v_max_f32_e32 v64, v168, v168
	v_max_f32_e32 v168, 0, v64
	v_exp_f32_e64 v169, -v168
	s_and_saveexec_b64 s[2:3], s[0:1]
	ds_write_b32 v216, v169 offset:6144
	s_or_b64 exec, exec, s[2:3]
	v_add_f32_e32 v220, v220, v168
	v_pk_add_f32 v[80:81], v[80:81], v[168:169] op_sel_hi:[1,0] neg_lo:[0,1] neg_hi:[0,1]
	v_pk_add_f32 v[96:97], v[96:97], v[168:169] op_sel_hi:[1,0] neg_lo:[0,1] neg_hi:[0,1]
	v_pk_add_f32 v[82:83], v[82:83], v[168:169] op_sel_hi:[1,0] neg_lo:[0,1] neg_hi:[0,1]
	v_pk_add_f32 v[98:99], v[98:99], v[168:169] op_sel_hi:[1,0] neg_lo:[0,1] neg_hi:[0,1]
	v_pk_add_f32 v[84:85], v[84:85], v[168:169] op_sel_hi:[1,0] neg_lo:[0,1] neg_hi:[0,1]
	v_pk_add_f32 v[100:101], v[100:101], v[168:169] op_sel_hi:[1,0] neg_lo:[0,1] neg_hi:[0,1]
	v_pk_add_f32 v[86:87], v[86:87], v[168:169] op_sel_hi:[1,0] neg_lo:[0,1] neg_hi:[0,1]
	v_pk_add_f32 v[102:103], v[102:103], v[168:169] op_sel_hi:[1,0] neg_lo:[0,1] neg_hi:[0,1]
	v_pk_add_f32 v[88:89], v[88:89], v[168:169] op_sel_hi:[1,0] neg_lo:[0,1] neg_hi:[0,1]
	v_pk_add_f32 v[104:105], v[104:105], v[168:169] op_sel_hi:[1,0] neg_lo:[0,1] neg_hi:[0,1]
	v_pk_add_f32 v[90:91], v[90:91], v[168:169] op_sel_hi:[1,0] neg_lo:[0,1] neg_hi:[0,1]
	v_pk_add_f32 v[106:107], v[106:107], v[168:169] op_sel_hi:[1,0] neg_lo:[0,1] neg_hi:[0,1]
	v_pk_add_f32 v[92:93], v[92:93], v[168:169] op_sel_hi:[1,0] neg_lo:[0,1] neg_hi:[0,1]
	v_pk_add_f32 v[108:109], v[108:109], v[168:169] op_sel_hi:[1,0] neg_lo:[0,1] neg_hi:[0,1]
	v_pk_add_f32 v[94:95], v[94:95], v[168:169] op_sel_hi:[1,0] neg_lo:[0,1] neg_hi:[0,1]
	v_pk_add_f32 v[110:111], v[110:111], v[168:169] op_sel_hi:[1,0] neg_lo:[0,1] neg_hi:[0,1]
	v_mul_f32_e32 v184, v184, v169
	ds_read_b128 v[168:171], v213 offset:6144
	ds_read_b128 v[172:175], v213 offset:6176
	ds_read_b128 v[176:179], v213 offset:6208
	ds_read_b128 v[180:183], v213 offset:6240
	v_xor_b32_e32 v64, 0x80000000, v220
	v_mov_b32_e32 v65, v64
	v_mov_b32_e32 v66, v64
	v_mov_b32_e32 v67, v64
	v_mov_b32_e32 v68, v64
	v_mov_b32_e32 v69, v64
	v_mov_b32_e32 v70, v64
	v_mov_b32_e32 v71, v64
	v_mov_b32_e32 v72, v64
	v_mov_b32_e32 v73, v64
	v_mov_b32_e32 v74, v64
	v_mov_b32_e32 v75, v64
	v_mov_b32_e32 v76, v64
	v_mov_b32_e32 v77, v64
	v_mov_b32_e32 v78, v64
	v_mov_b32_e32 v79, v64
	s_waitcnt lgkmcnt(0)
	v_pk_mul_f32 v[62:63], v[62:63], v[182:183]
	v_pk_mul_f32 v[58:59], v[58:59], v[178:179]
	v_pk_mul_f32 v[54:55], v[54:55], v[174:175]
	v_pk_mul_f32 v[50:51], v[50:51], v[170:171]
	v_pk_mul_f32 v[60:61], v[60:61], v[180:181]
	v_pk_mul_f32 v[56:57], v[56:57], v[176:177]
	v_pk_mul_f32 v[52:53], v[52:53], v[172:173]
	v_pk_mul_f32 v[48:49], v[48:49], v[168:169]
	v_pk_mul_f32 v[46:47], v[46:47], v[182:183]
	v_pk_mul_f32 v[42:43], v[42:43], v[178:179]
	v_pk_mul_f32 v[38:39], v[38:39], v[174:175]
	v_pk_mul_f32 v[34:35], v[34:35], v[170:171]
	v_pk_mul_f32 v[44:45], v[44:45], v[180:181]
	v_pk_mul_f32 v[40:41], v[40:41], v[176:177]
	v_pk_mul_f32 v[36:37], v[36:37], v[172:173]
	v_pk_mul_f32 v[32:33], v[32:33], v[168:169]
	v_pk_mul_f32 v[30:31], v[30:31], v[182:183]
	v_pk_mul_f32 v[26:27], v[26:27], v[178:179]
	v_pk_mul_f32 v[22:23], v[22:23], v[174:175]
	v_pk_mul_f32 v[18:19], v[18:19], v[170:171]
	v_pk_mul_f32 v[28:29], v[28:29], v[180:181]
	v_pk_mul_f32 v[24:25], v[24:25], v[176:177]
	v_pk_mul_f32 v[20:21], v[20:21], v[172:173]
	v_pk_mul_f32 v[16:17], v[16:17], v[168:169]
	v_pk_mul_f32 v[14:15], v[14:15], v[182:183]
	v_pk_mul_f32 v[10:11], v[10:11], v[178:179]
	v_pk_mul_f32 v[6:7], v[6:7], v[174:175]
	v_pk_mul_f32 v[2:3], v[2:3], v[170:171]
	v_pk_mul_f32 v[12:13], v[12:13], v[180:181]
	v_pk_mul_f32 v[8:9], v[8:9], v[176:177]
	v_pk_mul_f32 v[4:5], v[4:5], v[172:173]
	v_pk_mul_f32 v[0:1], v[0:1], v[168:169]
; __device__ __forceinline__ s16x4 vtr(const LAS unsigned char* p) { return __builtin_bit_cast(s16x4, __builtin_amdgcn_ds_read_tr16_b64_v4i16((LAS v4i16_t*)p)); }
; template <int DQK, int DV, bool HAS_BIAS>
; __device__ __forceinline__ void attn_tile(AttnState<DQK, DV>& st, const LAS unsigned char* Kt, const LAS unsigned char* Vt, int bias_mode, const LAS float* tab, int rel0, int nkeys, bool first, LAS float* wsf, int lane) {
;     ...
;     float sum0 = 0.f, sum1 = 0.f;
; #pragma unroll
;     for (int r = 0; r < 16; ++r) { p0[r] = __builtin_amdgcn_exp2f(p0[r]); p1[r] = __builtin_amdgcn_exp2f(p1[r]); sum0 += p0[r]; sum1 += p1[r]; }
;     st.l += sum0 + sum1;
;     bf16x8 pf[4];
;     pf[0] = pack8(p0[0], p0[1], p0[2], p0[3], p0[4], p0[5], p0[6], p0[7]);
;     pf[1] = pack8(p0[8], p0[9], p0[10], p0[11], p0[12], p0[13], p0[14], p0[15]);
;     pf[2] = pack8(p1[0], p1[1], p1[2], p1[3], p1[4], p1[5], p1[6], p1[7]);
;     pf[3] = pack8(p1[8], p1[9], p1[10], p1[11], p1[12], p1[13], p1[14], p1[15]);
;     __builtin_amdgcn_sched_barrier(0);
; #pragma unroll
;     for (int db = 0; db < NDB; ++db) {
;         if (db + 1 < NDB) {
; #pragma unroll
;             for (int s4 = 0; s4 < 4; ++s4) { vlo[(db + 1) & 1][s4] = vtr(vp + (16 * s4) * PV + (db + 1) * 64); vhi[(db + 1) & 1][s4] = vtr(vp + (16 * s4 + 8) * PV + (db + 1) * 64); }
;         }
; #pragma unroll
;         for (int s4 = 0; s4 < 4; ++s4) {
;             const s16x4 lo = vlo[db & 1][s4], h4 = vhi[db & 1][s4];
;             const bf16x8 vb = {lo[0], lo[1], lo[2], lo[3], h4[0], h4[1], h4[2], h4[3]};
;             st.o[db] = __builtin_amdgcn_mfma_f32_32x32x16_bf16(pf[s4], vb, st.o[db], 0, 0, 0);
;         }
;         __builtin_amdgcn_sched_barrier(0);
;     }
.LBB0_551:
	v_exp_f32_e32 v168, v80
	v_exp_f32_e32 v169, v81
	v_add_f32_e32 v200, 0, v168
	v_exp_f32_e32 v170, v82
	v_add_f32_e32 v200, v169, v200
	v_exp_f32_e32 v171, v83
	v_add_f32_e32 v200, v170, v200
	v_exp_f32_e32 v172, v84
	v_add_f32_e32 v200, v171, v200
	v_exp_f32_e32 v173, v85
	v_add_f32_e32 v200, v172, v200
	v_exp_f32_e32 v174, v86
	v_add_f32_e32 v200, v173, v200
	v_exp_f32_e32 v175, v87
	v_add_f32_e32 v200, v174, v200
	v_cvt_pk_bf16_f32 v80, v168, v169
	v_add_f32_e32 v200, v175, v200
	v_cvt_pk_bf16_f32 v81, v170, v171
	v_cvt_pk_bf16_f32 v82, v172, v173
	v_cvt_pk_bf16_f32 v83, v174, v175
	s_nop 1
	s_waitcnt lgkmcnt(8)
	v_mfma_f32_32x32x16_bf16 v[48:63], v[80:83], v[152:155], v[48:63]
	v_exp_f32_e32 v176, v88
	v_exp_f32_e32 v177, v89
	v_add_f32_e32 v200, v176, v200
	v_exp_f32_e32 v178, v90
	v_add_f32_e32 v200, v177, v200
	v_mfma_f32_32x32x16_bf16 v[32:47], v[80:83], v[156:159], v[32:47]
	v_exp_f32_e32 v179, v91
	v_add_f32_e32 v200, v178, v200
	v_exp_f32_e32 v180, v92
	v_add_f32_e32 v200, v179, v200
	v_exp_f32_e32 v181, v93
	v_mfma_f32_32x32x16_bf16 v[16:31], v[80:83], v[160:163], v[16:31]
	v_add_f32_e32 v200, v180, v200
	v_exp_f32_e32 v182, v94
	v_add_f32_e32 v200, v181, v200
	v_exp_f32_e32 v183, v95
	v_add_f32_e32 v200, v182, v200
	v_mfma_f32_32x32x16_bf16 v[0:15], v[80:83], v[164:167], v[0:15]
	v_cvt_pk_bf16_f32 v84, v176, v177
	v_add_f32_e32 v200, v183, v200
	v_cvt_pk_bf16_f32 v85, v178, v179
	v_cvt_pk_bf16_f32 v86, v180, v181
	v_cvt_pk_bf16_f32 v87, v182, v183
	ds_read_b64_tr_b16 v[152:153], v217 offset:57344
	ds_read_b64_tr_b16 v[154:155], v217 offset:59904
	ds_read_b64_tr_b16 v[156:157], v217 offset:57408
	ds_read_b64_tr_b16 v[158:159], v217 offset:59968
	ds_read_b64_tr_b16 v[160:161], v217 offset:57472
	ds_read_b64_tr_b16 v[162:163], v217 offset:60032
	ds_read_b64_tr_b16 v[164:165], v217 offset:57536
	ds_read_b64_tr_b16 v[166:167], v217 offset:60096
	s_waitcnt lgkmcnt(8)
	v_mfma_f32_32x32x16_bf16 v[48:63], v[84:87], v[226:229], v[48:63]
	v_exp_f32_e32 v168, v96
	v_exp_f32_e32 v169, v97
	v_add_f32_e32 v201, 0, v168
	v_exp_f32_e32 v170, v98
	v_add_f32_e32 v201, v169, v201
	v_mfma_f32_32x32x16_bf16 v[32:47], v[84:87], v[230:233], v[32:47]
	v_exp_f32_e32 v171, v99
	v_add_f32_e32 v201, v170, v201
	v_exp_f32_e32 v172, v100
	v_add_f32_e32 v201, v171, v201
	v_exp_f32_e32 v173, v101
	v_mfma_f32_32x32x16_bf16 v[16:31], v[84:87], v[234:237], v[16:31]
	v_add_f32_e32 v201, v172, v201
	v_exp_f32_e32 v174, v102
	v_add_f32_e32 v201, v173, v201
	v_exp_f32_e32 v175, v103
	v_add_f32_e32 v201, v174, v201
	v_mfma_f32_32x32x16_bf16 v[0:15], v[84:87], v[238:241], v[0:15]
	v_cvt_pk_bf16_f32 v88, v168, v169
	v_add_f32_e32 v201, v175, v201
	v_cvt_pk_bf16_f32 v89, v170, v171
	v_cvt_pk_bf16_f32 v90, v172, v173
	v_cvt_pk_bf16_f32 v91, v174, v175
	ds_read_b64_tr_b16 v[226:227], v217 offset:62464
	ds_read_b64_tr_b16 v[228:229], v217 offset:65024
	ds_read_b64_tr_b16 v[230:231], v217 offset:62528
	ds_read_b64_tr_b16 v[232:233], v217 offset:65088
	ds_read_b64_tr_b16 v[234:235], v217 offset:62592
	ds_read_b64_tr_b16 v[236:237], v217 offset:65152
	ds_read_b64_tr_b16 v[238:239], v217 offset:62656
	ds_read_b64_tr_b16 v[240:241], v217 offset:65216
	s_waitcnt lgkmcnt(8)
	v_mfma_f32_32x32x16_bf16 v[48:63], v[88:91], v[152:155], v[48:63]
	v_exp_f32_e32 v176, v104
	v_exp_f32_e32 v177, v105
	v_add_f32_e32 v201, v176, v201
	v_exp_f32_e32 v178, v106
	v_add_f32_e32 v201, v177, v201
	v_mfma_f32_32x32x16_bf16 v[32:47], v[88:91], v[156:159], v[32:47]
	v_exp_f32_e32 v179, v107
	v_add_f32_e32 v201, v178, v201
	v_exp_f32_e32 v180, v108
	v_add_f32_e32 v201, v179, v201
	v_exp_f32_e32 v181, v109
	v_mfma_f32_32x32x16_bf16 v[16:31], v[88:91], v[160:163], v[16:31]
	v_add_f32_e32 v201, v180, v201
	v_exp_f32_e32 v182, v110
	v_add_f32_e32 v201, v181, v201
	v_exp_f32_e32 v183, v111
	v_add_f32_e32 v201, v182, v201
	v_mfma_f32_32x32x16_bf16 v[0:15], v[88:91], v[164:167], v[0:15]
	v_cvt_pk_bf16_f32 v92, v176, v177
	v_add_f32_e32 v201, v183, v201
	v_cvt_pk_bf16_f32 v93, v178, v179
	v_cvt_pk_bf16_f32 v94, v180, v181
	v_cvt_pk_bf16_f32 v95, v182, v183
	s_waitcnt lgkmcnt(0)
	v_mfma_f32_32x32x16_bf16 v[48:63], v[92:95], v[226:229], v[48:63]
	v_add_f32_e32 v200, v201, v200
	v_mfma_f32_32x32x16_bf16 v[32:47], v[92:95], v[230:233], v[32:47]
	v_add_f32_e32 v184, v184, v200
	v_mfma_f32_32x32x16_bf16 v[16:31], v[92:95], v[234:237], v[16:31]
	v_mfma_f32_32x32x16_bf16 v[0:15], v[92:95], v[238:241], v[0:15]
	s_andn2_b64 vcc, exec, s[42:43]
	s_cbranch_vccz .LBB0_539
	s_branch .LBB0_540
